# attention softmax: s-m subtraction as packed in-place v_pk_add_f32 (2 elements per instruction), exp reads the element register directly
# speedup vs baseline: 1.0025x; 1.0025x over previous
; __device__ __forceinline__ unsigned pk2(float lo, float hi) { return pg8::cvt_pk_bf16(lo, hi); }
; __device__ __forceinline__ void attn_unit(const bf16* proj, unsigned char* ws, LAS unsigned char* lds, int a) {
;     ...
;             if (kb != n) {
;                 const int sgn = (kb < n) ? 1 : -1, dbase = sgn * (4 * fq - qi);
; #pragma unroll
;                 for (int kt = 0; kt < 8; ++kt)
; #pragma unroll
;                     for (int r = 0; r < 4; ++r) { const int dd = dbase + sgn * (16 * kt + r); st[rt][kt][r] += __builtin_bit_cast(float, (unsigned)(dd >> 31) & 0xF149F2CAu); }
;             }
;             float mx = -1e30f;
; #pragma unroll
;             for (int kt = 0; kt < 8; ++kt)
; #pragma unroll
;                 for (int r = 0; r < 4; ++r) mx = fmaxf(mx, st[rt][kt][r]);
;             mx = fmaxf(mx, __shfl_xor(mx, 16)); mx = fmaxf(mx, __shfl_xor(mx, 32));
;             const float mnew = fmaxf(mrow[rt], mx), alpha = __builtin_amdgcn_exp2f(mrow[rt] - mnew);
;             mrow[rt] = mnew; float ls = lrow[rt] * alpha;
; #pragma unroll
;             for (int dt = 0; dt < 8; ++dt) O[rt][dt] *= alpha;
; #pragma unroll
;             for (int kt = 0; kt < 8; ++kt)
; #pragma unroll
;                 for (int r = 0; r < 4; ++r) { const float p = __builtin_amdgcn_exp2f(st[rt][kt][r] - mnew); st[rt][kt][r] = p; ls += p; }
;             lrow[rt] = ls;
; #pragma unroll
;             for (int tp = 0; tp < 4; ++tp) {
;                 v4u w; w.x = pk2(st[rt][2 * tp][0], st[rt][2 * tp][1]); w.y = pk2(st[rt][2 * tp][2], st[rt][2 * tp][3]);
;                 w.z = pk2(st[rt][2 * tp + 1][0], st[rt][2 * tp + 1][1]); w.w = pk2(st[rt][2 * tp + 1][2], st[rt][2 * tp + 1][3]);
;                 pb[rt][tp] = __builtin_bit_cast(bf16x8, w);
;             }
.LBB0_610:
	v_max3_f32 v207, v92, s67, v93
	v_max3_f32 v207, v207, v94, v95
	v_max3_f32 v207, v207, v100, v101
	v_max3_f32 v207, v207, v102, v103
	v_max3_f32 v207, v207, v104, v105
	v_max3_f32 v207, v207, v106, v107
	v_max3_f32 v207, v207, v108, v109
	v_max3_f32 v207, v207, v110, v111
	v_max3_f32 v207, v207, v144, v145
	v_max3_f32 v207, v207, v146, v147
	v_max3_f32 v207, v207, v148, v149
	v_max3_f32 v207, v207, v150, v151
	v_max3_f32 v207, v207, v152, v153
	v_max3_f32 v207, v207, v154, v155
	v_max3_f32 v207, v207, v156, v157
	v_max3_f32 v207, v207, v158, v159
	ds_bpermute_b32 v238, v203, v207
	s_andn2_b64 vcc, exec, s[56:57]
	s_waitcnt lgkmcnt(0)
	v_max_f32_e32 v238, v238, v238
	v_max_f32_e32 v207, v207, v238
	ds_bpermute_b32 v238, v204, v207
	s_waitcnt lgkmcnt(0)
	v_max3_f32 v207, v209, v207, v238
	v_mov_b32_e32 v254, v207
	v_pk_add_f32 v[92:93], v[92:93], v[254:255] op_sel_hi:[1,0] neg_lo:[0,1] neg_hi:[0,1]
	v_pk_add_f32 v[94:95], v[94:95], v[254:255] op_sel_hi:[1,0] neg_lo:[0,1] neg_hi:[0,1]
	v_pk_add_f32 v[100:101], v[100:101], v[254:255] op_sel_hi:[1,0] neg_lo:[0,1] neg_hi:[0,1]
	v_pk_add_f32 v[102:103], v[102:103], v[254:255] op_sel_hi:[1,0] neg_lo:[0,1] neg_hi:[0,1]
	v_pk_add_f32 v[104:105], v[104:105], v[254:255] op_sel_hi:[1,0] neg_lo:[0,1] neg_hi:[0,1]
	v_pk_add_f32 v[106:107], v[106:107], v[254:255] op_sel_hi:[1,0] neg_lo:[0,1] neg_hi:[0,1]
	v_pk_add_f32 v[108:109], v[108:109], v[254:255] op_sel_hi:[1,0] neg_lo:[0,1] neg_hi:[0,1]
	v_pk_add_f32 v[110:111], v[110:111], v[254:255] op_sel_hi:[1,0] neg_lo:[0,1] neg_hi:[0,1]
	v_pk_add_f32 v[144:145], v[144:145], v[254:255] op_sel_hi:[1,0] neg_lo:[0,1] neg_hi:[0,1]
	v_pk_add_f32 v[146:147], v[146:147], v[254:255] op_sel_hi:[1,0] neg_lo:[0,1] neg_hi:[0,1]
	v_pk_add_f32 v[148:149], v[148:149], v[254:255] op_sel_hi:[1,0] neg_lo:[0,1] neg_hi:[0,1]
	v_pk_add_f32 v[150:151], v[150:151], v[254:255] op_sel_hi:[1,0] neg_lo:[0,1] neg_hi:[0,1]
	v_pk_add_f32 v[152:153], v[152:153], v[254:255] op_sel_hi:[1,0] neg_lo:[0,1] neg_hi:[0,1]
	v_pk_add_f32 v[154:155], v[154:155], v[254:255] op_sel_hi:[1,0] neg_lo:[0,1] neg_hi:[0,1]
	v_pk_add_f32 v[156:157], v[156:157], v[254:255] op_sel_hi:[1,0] neg_lo:[0,1] neg_hi:[0,1]
	v_pk_add_f32 v[158:159], v[158:159], v[254:255] op_sel_hi:[1,0] neg_lo:[0,1] neg_hi:[0,1]
	v_exp_f32_e32 v238, v92
	v_exp_f32_e32 v243, v101
	v_exp_f32_e32 v244, v102
	v_exp_f32_e32 v245, v103
	v_exp_f32_e32 v246, v104
	v_exp_f32_e32 v247, v105
	v_exp_f32_e32 v248, v106
	v_exp_f32_e32 v249, v107
	v_exp_f32_e32 v250, v108
	v_exp_f32_e32 v251, v109
	v_exp_f32_e32 v252, v110
	v_exp_f32_e32 v253, v111
	v_exp_f32_e32 v144, v144
	v_exp_f32_e32 v145, v145
	v_exp_f32_e32 v146, v146
	v_exp_f32_e32 v147, v147
	v_exp_f32_e32 v148, v148
	v_exp_f32_e32 v149, v149
	v_exp_f32_e32 v150, v150
	v_exp_f32_e32 v151, v151
	v_exp_f32_e32 v152, v152
	v_exp_f32_e32 v153, v153
	v_exp_f32_e32 v154, v154
	v_exp_f32_e32 v155, v155
	v_exp_f32_e32 v156, v156
	v_exp_f32_e32 v157, v157
	v_exp_f32_e32 v158, v158
	v_exp_f32_e32 v239, v93
	v_exp_f32_e32 v240, v94
	v_exp_f32_e32 v241, v95
	v_exp_f32_e32 v242, v100
	v_exp_f32_e32 v159, v159
	v_cvt_pk_bf16_f32 v108, v238, v239
	v_cvt_pk_bf16_f32 v109, v240, v241
	v_cvt_pk_bf16_f32 v110, v242, v243
	v_cvt_pk_bf16_f32 v111, v244, v245
	v_cvt_pk_bf16_f32 v104, v246, v247
	v_cvt_pk_bf16_f32 v105, v248, v249
	v_cvt_pk_bf16_f32 v106, v250, v251
	v_cvt_pk_bf16_f32 v107, v252, v253
	v_cvt_pk_bf16_f32 v100, v144, v145
	v_cvt_pk_bf16_f32 v101, v146, v147
	v_cvt_pk_bf16_f32 v102, v148, v149
	v_cvt_pk_bf16_f32 v103, v150, v151
	v_cvt_pk_bf16_f32 v92, v152, v153
	v_cvt_pk_bf16_f32 v93, v154, v155
	v_cvt_pk_bf16_f32 v94, v156, v157
	v_cvt_pk_bf16_f32 v95, v158, v159
	s_cbranch_vccnz .LBB0_612
	s_cmp_lt_u32 s70, s69
	s_cbranch_scc0 .Lam_b_next
	v_cmp_gt_i32_e32 vcc, 0, v181
	v_cndmask_b32_e32 v136, v136, v171, vcc
	v_cmp_gt_i32_e32 vcc, -1, v181
	v_cndmask_b32_e32 v137, v137, v171, vcc
	v_cmp_gt_i32_e32 vcc, -2, v181
	v_cndmask_b32_e32 v138, v138, v171, vcc
	v_cmp_gt_i32_e32 vcc, -3, v181
	v_cndmask_b32_e32 v139, v139, v171, vcc
	v_cmp_gt_i32_e32 vcc, -16, v181
	v_cndmask_b32_e32 v132, v132, v171, vcc
	v_cmp_gt_i32_e32 vcc, 0xffffffef, v181
	v_cndmask_b32_e32 v133, v133, v171, vcc
	v_cmp_gt_i32_e32 vcc, 0xffffffee, v181
	v_cndmask_b32_e32 v134, v134, v171, vcc
	v_cmp_gt_i32_e32 vcc, 0xffffffed, v181
	v_cndmask_b32_e32 v135, v135, v171, vcc
	v_cmp_gt_i32_e32 vcc, 0xffffffe0, v181
	v_cndmask_b32_e32 v128, v128, v171, vcc
	v_cmp_gt_i32_e32 vcc, 0xffffffdf, v181
	v_cndmask_b32_e32 v129, v129, v171, vcc
	v_cmp_gt_i32_e32 vcc, 0xffffffde, v181
	v_cndmask_b32_e32 v130, v130, v171, vcc
	v_cmp_gt_i32_e32 vcc, 0xffffffdd, v181
	v_cndmask_b32_e32 v131, v131, v171, vcc
	v_cmp_gt_i32_e32 vcc, 0xffffffd0, v181
	v_cndmask_b32_e32 v124, v124, v171, vcc
	v_cmp_gt_i32_e32 vcc, 0xffffffcf, v181
	v_cndmask_b32_e32 v125, v125, v171, vcc
	v_cmp_gt_i32_e32 vcc, 0xffffffce, v181
	v_cndmask_b32_e32 v126, v126, v171, vcc
	v_cmp_gt_i32_e32 vcc, 0xffffffcd, v181
	v_cndmask_b32_e32 v127, v127, v171, vcc
	v_cmp_gt_i32_e32 vcc, 0xffffffc0, v181
	v_cndmask_b32_e32 v120, v120, v171, vcc
	v_cmp_gt_i32_e32 vcc, 0xffffffbf, v181
	v_cndmask_b32_e32 v121, v121, v171, vcc
	v_cmp_gt_i32_e32 vcc, 0xffffffbe, v181
	v_cndmask_b32_e32 v122, v122, v171, vcc
	v_cmp_gt_i32_e32 vcc, 0xffffffbd, v181
	v_cndmask_b32_e32 v123, v123, v171, vcc
	v_cmp_gt_i32_e32 vcc, 0xffffffb0, v181
	v_cndmask_b32_e32 v116, v116, v171, vcc
	v_cmp_gt_i32_e32 vcc, 0xffffffaf, v181
	v_cndmask_b32_e32 v117, v117, v171, vcc
	v_cmp_gt_i32_e32 vcc, 0xffffffae, v181
	v_cndmask_b32_e32 v118, v118, v171, vcc
	v_cmp_gt_i32_e32 vcc, 0xffffffad, v181
	v_cndmask_b32_e32 v119, v119, v171, vcc
	v_cmp_gt_i32_e32 vcc, 0xffffffa0, v181
	v_cndmask_b32_e32 v112, v112, v171, vcc
	v_cmp_gt_i32_e32 vcc, 0xffffff9f, v181
	v_cndmask_b32_e32 v113, v113, v171, vcc
	v_cmp_gt_i32_e32 vcc, 0xffffff9e, v181
	v_cndmask_b32_e32 v114, v114, v171, vcc
	v_cmp_gt_i32_e32 vcc, 0xffffff9d, v181
	v_cndmask_b32_e32 v115, v115, v171, vcc
	v_cmp_gt_i32_e32 vcc, 16, v181
	v_cndmask_b32_e32 v140, v140, v171, vcc
	v_cmp_gt_i32_e32 vcc, 15, v181
	v_cndmask_b32_e32 v141, v141, v171, vcc
	v_cmp_gt_i32_e32 vcc, 14, v181
	v_cndmask_b32_e32 v142, v142, v171, vcc
	v_cmp_gt_i32_e32 vcc, 13, v181
	v_cndmask_b32_e32 v143, v143, v171, vcc
	s_branch .LBB0_612

; __device__ __forceinline__ void attn_unit(const bf16* proj, unsigned char* ws, LAS unsigned char* lds, int a) {
;     ...
;             const float mnew = fmaxf(mrow[rt], mx), alpha = __builtin_amdgcn_exp2f(mrow[rt] - mnew);
;             mrow[rt] = mnew; float ls = lrow[rt] * alpha;
; #pragma unroll
;             for (int dt = 0; dt < 8; ++dt) O[rt][dt] *= alpha;
; #pragma unroll
;             for (int kt = 0; kt < 8; ++kt)
; #pragma unroll
;                 for (int r = 0; r < 4; ++r) { const float p = __builtin_amdgcn_exp2f(st[rt][kt][r] - mnew); st[rt][kt][r] = p; ls += p; }
;             lrow[rt] = ls;
.LBB0_612:
	v_sub_f32_e32 v209, v209, v207
	v_exp_f32_e32 v210, v209
	s_add_i32 s70, s70, 1
	s_addk_i32 s51, 0x80
	s_and_b64 vcc, exec, s[54:55]
	v_fmac_f32_e32 v238, v179, v210
	v_add_f32_e32 v179, v239, v238
	v_add_f32_e32 v179, v240, v179
	v_add_f32_e32 v179, v241, v179
	v_add_f32_e32 v179, v242, v179
	v_add_f32_e32 v179, v243, v179
	v_add_f32_e32 v179, v244, v179
	v_add_f32_e32 v179, v245, v179
	v_add_f32_e32 v179, v246, v179
	v_add_f32_e32 v179, v247, v179
	v_add_f32_e32 v179, v248, v179
	v_add_f32_e32 v179, v249, v179
	v_add_f32_e32 v179, v250, v179
	v_add_f32_e32 v179, v251, v179
	v_add_f32_e32 v179, v252, v179
	v_add_f32_e32 v179, v253, v179
	v_add_f32_e32 v144, v144, v179
	v_add_f32_e32 v144, v145, v144
	v_add_f32_e32 v144, v146, v144
	v_add_f32_e32 v144, v147, v144
	v_add_f32_e32 v144, v148, v144
	v_add_f32_e32 v144, v149, v144
	v_add_f32_e32 v144, v150, v144
	v_add_f32_e32 v144, v151, v144
	v_add_f32_e32 v144, v152, v144
	v_add_f32_e32 v144, v153, v144
	v_add_f32_e32 v144, v154, v144
	v_add_f32_e32 v144, v155, v144
	v_add_f32_e32 v144, v156, v144
	v_add_f32_e32 v144, v157, v144
	v_add_f32_e32 v144, v158, v144
	v_add_f32_e32 v179, v159, v144
	v_max3_f32 v144, v140, s67, v141
	v_max3_f32 v144, v144, v142, v143
	v_max3_f32 v144, v144, v136, v137
	v_max3_f32 v144, v144, v138, v139
	v_max3_f32 v144, v144, v132, v133
	v_max3_f32 v144, v144, v134, v135
	v_max3_f32 v144, v144, v128, v129
	v_max3_f32 v144, v144, v130, v131
	v_max3_f32 v144, v144, v124, v125
	v_max3_f32 v144, v144, v126, v127
	v_max3_f32 v144, v144, v120, v121
	v_max3_f32 v144, v144, v122, v123
	v_max3_f32 v144, v144, v116, v117
	v_max3_f32 v144, v144, v118, v119
	v_max3_f32 v144, v144, v112, v113
	v_max3_f32 v144, v144, v114, v115
	ds_bpermute_b32 v145, v203, v144
	v_pk_mul_f32 v[66:67], v[66:67], v[210:211] op_sel_hi:[1,0]
	v_pk_mul_f32 v[64:65], v[64:65], v[210:211] op_sel_hi:[1,0]
	v_pk_mul_f32 v[62:63], v[62:63], v[210:211] op_sel_hi:[1,0]
	v_pk_mul_f32 v[60:61], v[60:61], v[210:211] op_sel_hi:[1,0]
	s_waitcnt lgkmcnt(0)
	v_max_f32_e32 v145, v145, v145
	v_max_f32_e32 v144, v144, v145
	ds_bpermute_b32 v145, v204, v144
	v_pk_mul_f32 v[70:71], v[70:71], v[210:211] op_sel_hi:[1,0]
	v_pk_mul_f32 v[68:69], v[68:69], v[210:211] op_sel_hi:[1,0]
	v_pk_mul_f32 v[74:75], v[74:75], v[210:211] op_sel_hi:[1,0]
	v_pk_mul_f32 v[72:73], v[72:73], v[210:211] op_sel_hi:[1,0]
	s_waitcnt lgkmcnt(0)
	v_max3_f32 v148, v208, v144, v145
	v_sub_f32_e32 v144, v208, v148
	v_exp_f32_e32 v150, v144
	v_pk_add_f32 v[112:113], v[112:113], v[148:149] op_sel_hi:[1,0] neg_lo:[0,1] neg_hi:[0,1]
	v_pk_add_f32 v[114:115], v[114:115], v[148:149] op_sel_hi:[1,0] neg_lo:[0,1] neg_hi:[0,1]
	v_pk_add_f32 v[116:117], v[116:117], v[148:149] op_sel_hi:[1,0] neg_lo:[0,1] neg_hi:[0,1]
	v_pk_add_f32 v[118:119], v[118:119], v[148:149] op_sel_hi:[1,0] neg_lo:[0,1] neg_hi:[0,1]
	v_pk_add_f32 v[120:121], v[120:121], v[148:149] op_sel_hi:[1,0] neg_lo:[0,1] neg_hi:[0,1]
	v_pk_add_f32 v[122:123], v[122:123], v[148:149] op_sel_hi:[1,0] neg_lo:[0,1] neg_hi:[0,1]
	v_pk_add_f32 v[124:125], v[124:125], v[148:149] op_sel_hi:[1,0] neg_lo:[0,1] neg_hi:[0,1]
	v_pk_add_f32 v[126:127], v[126:127], v[148:149] op_sel_hi:[1,0] neg_lo:[0,1] neg_hi:[0,1]
	v_pk_add_f32 v[128:129], v[128:129], v[148:149] op_sel_hi:[1,0] neg_lo:[0,1] neg_hi:[0,1]
	v_pk_add_f32 v[130:131], v[130:131], v[148:149] op_sel_hi:[1,0] neg_lo:[0,1] neg_hi:[0,1]
	v_pk_add_f32 v[132:133], v[132:133], v[148:149] op_sel_hi:[1,0] neg_lo:[0,1] neg_hi:[0,1]
	v_pk_add_f32 v[134:135], v[134:135], v[148:149] op_sel_hi:[1,0] neg_lo:[0,1] neg_hi:[0,1]
	v_pk_add_f32 v[136:137], v[136:137], v[148:149] op_sel_hi:[1,0] neg_lo:[0,1] neg_hi:[0,1]
	v_pk_add_f32 v[138:139], v[138:139], v[148:149] op_sel_hi:[1,0] neg_lo:[0,1] neg_hi:[0,1]
	v_pk_add_f32 v[140:141], v[140:141], v[148:149] op_sel_hi:[1,0] neg_lo:[0,1] neg_hi:[0,1]
	v_pk_add_f32 v[142:143], v[142:143], v[148:149] op_sel_hi:[1,0] neg_lo:[0,1] neg_hi:[0,1]
	v_exp_f32_e32 v136, v136
	v_pk_mul_f32 v[144:145], v[84:85], v[150:151] op_sel_hi:[1,0]
	v_pk_mul_f32 v[146:147], v[86:87], v[150:151] op_sel_hi:[1,0]
	v_exp_f32_e32 v84, v140
	v_exp_f32_e32 v86, v141
	v_exp_f32_e32 v87, v142
	v_exp_f32_e32 v140, v143
	v_fma_f32 v85, v176, v150, v84
	v_add_f32_e32 v85, v86, v85
	v_exp_f32_e32 v137, v137
	v_add_f32_e32 v85, v87, v85
	v_exp_f32_e32 v138, v138
	v_add_f32_e32 v85, v140, v85
	v_exp_f32_e32 v139, v139
	v_add_f32_e32 v85, v136, v85
	v_exp_f32_e32 v132, v132
	v_add_f32_e32 v85, v137, v85
	v_exp_f32_e32 v133, v133
	v_add_f32_e32 v85, v138, v85
	v_exp_f32_e32 v134, v134
	v_add_f32_e32 v85, v139, v85
	v_exp_f32_e32 v135, v135
	v_add_f32_e32 v85, v132, v85
	v_exp_f32_e32 v128, v128
	v_add_f32_e32 v85, v133, v85
	v_exp_f32_e32 v129, v129
	v_add_f32_e32 v85, v134, v85
	v_exp_f32_e32 v130, v130
	v_add_f32_e32 v85, v135, v85
	v_exp_f32_e32 v131, v131
	v_add_f32_e32 v85, v128, v85
	v_exp_f32_e32 v124, v124
	v_add_f32_e32 v85, v129, v85
	v_exp_f32_e32 v125, v125
	v_add_f32_e32 v85, v130, v85
	v_exp_f32_e32 v126, v126
	v_add_f32_e32 v85, v131, v85
	v_exp_f32_e32 v127, v127
	v_add_f32_e32 v85, v124, v85
	v_exp_f32_e32 v141, v120
	v_add_f32_e32 v85, v125, v85
	v_exp_f32_e32 v142, v121
	v_add_f32_e32 v85, v126, v85
	v_exp_f32_e32 v143, v122
	v_add_f32_e32 v85, v127, v85
	v_exp_f32_e32 v149, v123
	v_pk_mul_f32 v[38:39], v[38:39], v[150:151] op_sel_hi:[1,0]
	v_pk_mul_f32 v[36:37], v[36:37], v[150:151] op_sel_hi:[1,0]
	v_pk_mul_f32 v[34:35], v[34:35], v[150:151] op_sel_hi:[1,0]
	v_pk_mul_f32 v[32:33], v[32:33], v[150:151] op_sel_hi:[1,0]
	v_pk_mul_f32 v[42:43], v[42:43], v[150:151] op_sel_hi:[1,0]
	v_pk_mul_f32 v[40:41], v[40:41], v[150:151] op_sel_hi:[1,0]
; #define LAS __attribute__((address_space(3)))
; __device__ __forceinline__ unsigned pk2(float lo, float hi) { return pg8::cvt_pk_bf16(lo, hi); }
; __device__ __forceinline__ void attn_unit(const bf16* proj, unsigned char* ws, LAS unsigned char* lds, int a) {
;     ...
;             const float mnew = fmaxf(mrow[rt], mx), alpha = __builtin_amdgcn_exp2f(mrow[rt] - mnew);
;             mrow[rt] = mnew; float ls = lrow[rt] * alpha;
; #pragma unroll
;             for (int dt = 0; dt < 8; ++dt) O[rt][dt] *= alpha;
; #pragma unroll
;             for (int kt = 0; kt < 8; ++kt)
; #pragma unroll
;                 for (int r = 0; r < 4; ++r) { const float p = __builtin_amdgcn_exp2f(st[rt][kt][r] - mnew); st[rt][kt][r] = p; ls += p; }
;             lrow[rt] = ls;
; #pragma unroll
;             for (int tp = 0; tp < 4; ++tp) {
;                 v4u w; w.x = pk2(st[rt][2 * tp][0], st[rt][2 * tp][1]); w.y = pk2(st[rt][2 * tp][2], st[rt][2 * tp][3]);
;                 w.z = pk2(st[rt][2 * tp + 1][0], st[rt][2 * tp + 1][1]); w.w = pk2(st[rt][2 * tp + 1][2], st[rt][2 * tp + 1][3]);
;                 pb[rt][tp] = __builtin_bit_cast(bf16x8, w);
;             }
;         }
; #pragma unroll
;         for (int dt = 0; dt < 8; ++dt)
; #pragma unroll
;             for (int tp = 0; tp < 4; ++tp) {
;                 const LAS unsigned char* p0 = VS + (32 * tp + 4 * fq + (fr >> 2)) * V_STRIDE + (16 * dt + 4 * (fr & 3)) * 2;
;                 const bf16x8 vf = tr_frag(p0, p0 + 16 * V_STRIDE);
;                 O[0][dt] = __builtin_amdgcn_mfma_f32_16x16x32_bf16(vf, pb[0][tp], O[0][dt], 0, 0, 0);
;                 O[1][dt] = __builtin_amdgcn_mfma_f32_16x16x32_bf16(vf, pb[1][tp], O[1][dt], 0, 0, 0);
	v_pk_mul_f32 v[46:47], v[46:47], v[150:151] op_sel_hi:[1,0]
	v_pk_mul_f32 v[44:45], v[44:45], v[150:151] op_sel_hi:[1,0]
	v_pk_mul_f32 v[50:51], v[50:51], v[150:151] op_sel_hi:[1,0]
	v_pk_mul_f32 v[48:49], v[48:49], v[150:151] op_sel_hi:[1,0]
	v_pk_mul_f32 v[54:55], v[54:55], v[150:151] op_sel_hi:[1,0]
	v_pk_mul_f32 v[52:53], v[52:53], v[150:151] op_sel_hi:[1,0]
	v_pk_mul_f32 v[58:59], v[58:59], v[150:151] op_sel_hi:[1,0]
	v_pk_mul_f32 v[56:57], v[56:57], v[150:151] op_sel_hi:[1,0]
	v_add_f32_e32 v85, v141, v85
	v_exp_f32_e32 v150, v116
	v_add_f32_e32 v85, v142, v85
	v_exp_f32_e32 v151, v117
	v_add_f32_e32 v85, v143, v85
	v_exp_f32_e32 v152, v118
	v_add_f32_e32 v85, v149, v85
	v_exp_f32_e32 v153, v119
	v_add_f32_e32 v85, v150, v85
	v_exp_f32_e32 v154, v112
	v_add_f32_e32 v85, v151, v85
	v_exp_f32_e32 v155, v113
	v_add_f32_e32 v85, v152, v85
	v_exp_f32_e32 v156, v114
	v_add_f32_e32 v85, v153, v85
	v_exp_f32_e32 v157, v115
	v_add_f32_e32 v85, v154, v85
	v_add_f32_e32 v85, v155, v85
	v_add_f32_e32 v85, v156, v85
	v_add_f32_e32 v176, v157, v85
	v_cvt_pk_bf16_f32 v120, v84, v86
	v_cvt_pk_bf16_f32 v121, v87, v140
	v_cvt_pk_bf16_f32 v122, v136, v137
	v_cvt_pk_bf16_f32 v123, v138, v139
	v_cvt_pk_bf16_f32 v116, v132, v133
	v_cvt_pk_bf16_f32 v117, v134, v135
	v_cvt_pk_bf16_f32 v118, v128, v129
	v_cvt_pk_bf16_f32 v119, v130, v131
	v_cvt_pk_bf16_f32 v112, v124, v125
	v_cvt_pk_bf16_f32 v113, v126, v127
	v_cvt_pk_bf16_f32 v114, v141, v142
	v_cvt_pk_bf16_f32 v115, v143, v149
	v_cvt_pk_bf16_f32 v84, v150, v151
	v_cvt_pk_bf16_f32 v85, v152, v153
	v_cvt_pk_bf16_f32 v86, v154, v155
	v_cvt_pk_bf16_f32 v87, v156, v157
	ds_read_b64_tr_b16 v[124:125], v202
	ds_read_b64_tr_b16 v[126:127], v202 offset:4608
	ds_read_b64_tr_b16 v[128:129], v202 offset:9216
	ds_read_b64_tr_b16 v[130:131], v202 offset:13824
	ds_read_b64_tr_b16 v[132:133], v202 offset:18432
	ds_read_b64_tr_b16 v[134:135], v202 offset:23040
	v_mul_f32_e64 v78, v78, v210
	v_mul_f32_e64 v79, v79, v210
	v_pk_mul_f32 v[76:77], v[76:77], v[210:211] op_sel_hi:[1,0]
	v_pk_mul_f32 v[82:83], v[82:83], v[210:211] op_sel_hi:[1,0]
	v_pk_mul_f32 v[80:81], v[80:81], v[210:211] op_sel_hi:[1,0]
	v_pk_mul_f32 v[90:91], v[90:91], v[210:211] op_sel_hi:[1,0]
	v_mul_f32_e64 v88, v88, v210
	v_mul_f32_e64 v89, v89, v210
	v_pk_mul_f32 v[98:99], v[98:99], v[210:211] op_sel_hi:[1,0]
	v_pk_mul_f32 v[96:97], v[96:97], v[210:211] op_sel_hi:[1,0]
	ds_read_b64_tr_b16 v[136:137], v202 offset:27648
	ds_read_b64_tr_b16 v[138:139], v202 offset:32256
	s_waitcnt lgkmcnt(6)
	v_mfma_f32_16x16x32_bf16 v[64:67], v[124:127], v[108:111], v[64:67]
	v_mfma_f32_16x16x32_bf16 v[36:39], v[124:127], v[120:123], v[36:39]
	ds_read_b64_tr_b16 v[124:125], v202 offset:32
	ds_read_b64_tr_b16 v[126:127], v202 offset:4640
	s_waitcnt lgkmcnt(6)
	v_mfma_f32_16x16x32_bf16 v[64:67], v[128:131], v[104:107], v[64:67]
	v_mfma_f32_16x16x32_bf16 v[36:39], v[128:131], v[116:119], v[36:39]
	ds_read_b64_tr_b16 v[128:129], v202 offset:9248
	ds_read_b64_tr_b16 v[130:131], v202 offset:13856
	s_waitcnt lgkmcnt(6)
	v_mfma_f32_16x16x32_bf16 v[64:67], v[132:135], v[100:103], v[64:67]
	v_mfma_f32_16x16x32_bf16 v[36:39], v[132:135], v[112:115], v[36:39]
	ds_read_b64_tr_b16 v[132:133], v202 offset:18464
	ds_read_b64_tr_b16 v[134:135], v202 offset:23072
	s_waitcnt lgkmcnt(6)
	v_mfma_f32_16x16x32_bf16 v[64:67], v[136:139], v[92:95], v[64:67]
	v_mfma_f32_16x16x32_bf16 v[36:39], v[136:139], v[84:87], v[36:39]
	ds_read_b64_tr_b16 v[136:137], v202 offset:27680
	ds_read_b64_tr_b16 v[138:139], v202 offset:32288
	s_waitcnt lgkmcnt(6)
	v_mfma_f32_16x16x32_bf16 v[60:63], v[124:127], v[108:111], v[60:63]
	v_mfma_f32_16x16x32_bf16 v[32:35], v[124:127], v[120:123], v[32:35]
	ds_read_b64_tr_b16 v[124:125], v202 offset:64
	ds_read_b64_tr_b16 v[126:127], v202 offset:4672
	s_waitcnt lgkmcnt(6)
	v_mfma_f32_16x16x32_bf16 v[60:63], v[128:131], v[104:107], v[60:63]
	v_mfma_f32_16x16x32_bf16 v[32:35], v[128:131], v[116:119], v[32:35]
	ds_read_b64_tr_b16 v[128:129], v202 offset:9280
	ds_read_b64_tr_b16 v[130:131], v202 offset:13888
	s_waitcnt lgkmcnt(6)
	v_mfma_f32_16x16x32_bf16 v[60:63], v[132:135], v[100:103], v[60:63]
	v_mfma_f32_16x16x32_bf16 v[32:35], v[132:135], v[112:115], v[32:35]
	ds_read_b64_tr_b16 v[132:133], v202 offset:18496
	ds_read_b64_tr_b16 v[134:135], v202 offset:23104
	s_waitcnt lgkmcnt(6)
	v_mfma_f32_16x16x32_bf16 v[60:63], v[136:139], v[92:95], v[60:63]
	v_mfma_f32_16x16x32_bf16 v[32:35], v[136:139], v[84:87], v[32:35]
	ds_read_b64_tr_b16 v[136:137], v202 offset:27712
	ds_read_b64_tr_b16 v[138:139], v202 offset:32320
	s_waitcnt lgkmcnt(6)
	v_mfma_f32_16x16x32_bf16 v[68:71], v[124:127], v[108:111], v[68:71]
	v_mfma_f32_16x16x32_bf16 v[40:43], v[124:127], v[120:123], v[40:43]
	ds_read_b64_tr_b16 v[124:125], v202 offset:96
	ds_read_b64_tr_b16 v[126:127], v202 offset:4704
	s_waitcnt lgkmcnt(6)
	v_mfma_f32_16x16x32_bf16 v[68:71], v[128:131], v[104:107], v[68:71]
	v_mfma_f32_16x16x32_bf16 v[40:43], v[128:131], v[116:119], v[40:43]
	ds_read_b64_tr_b16 v[128:129], v202 offset:9312
	ds_read_b64_tr_b16 v[130:131], v202 offset:13920
	s_waitcnt lgkmcnt(6)
	v_mfma_f32_16x16x32_bf16 v[68:71], v[132:135], v[100:103], v[68:71]
	v_mfma_f32_16x16x32_bf16 v[40:43], v[132:135], v[112:115], v[40:43]
	ds_read_b64_tr_b16 v[132:133], v202 offset:18528
	ds_read_b64_tr_b16 v[134:135], v202 offset:23136
	s_waitcnt lgkmcnt(6)
; #define LAS __attribute__((address_space(3)))
; __device__ __forceinline__ void attn_unit(const bf16* proj, unsigned char* ws, LAS unsigned char* lds, int a) {
;     ...
; #pragma unroll
;         for (int dt = 0; dt < 8; ++dt)
; #pragma unroll
;             for (int tp = 0; tp < 4; ++tp) {
;                 const LAS unsigned char* p0 = VS + (32 * tp + 4 * fq + (fr >> 2)) * V_STRIDE + (16 * dt + 4 * (fr & 3)) * 2;
;                 const bf16x8 vf = tr_frag(p0, p0 + 16 * V_STRIDE);
;                 O[0][dt] = __builtin_amdgcn_mfma_f32_16x16x32_bf16(vf, pb[0][tp], O[0][dt], 0, 0, 0);
;                 O[1][dt] = __builtin_amdgcn_mfma_f32_16x16x32_bf16(vf, pb[1][tp], O[1][dt], 0, 0, 0);
;             }
	v_mfma_f32_16x16x32_bf16 v[68:71], v[136:139], v[92:95], v[68:71]
	v_mfma_f32_16x16x32_bf16 v[40:43], v[136:139], v[84:87], v[40:43]
	ds_read_b64_tr_b16 v[136:137], v202 offset:27744
	ds_read_b64_tr_b16 v[138:139], v202 offset:32352
	s_waitcnt lgkmcnt(6)
	v_mfma_f32_16x16x32_bf16 v[72:75], v[124:127], v[108:111], v[72:75]
	v_mfma_f32_16x16x32_bf16 v[44:47], v[124:127], v[120:123], v[44:47]
	ds_read_b64_tr_b16 v[124:125], v202 offset:128
	ds_read_b64_tr_b16 v[126:127], v202 offset:4736
	s_waitcnt lgkmcnt(6)
	v_mfma_f32_16x16x32_bf16 v[72:75], v[128:131], v[104:107], v[72:75]
	v_mfma_f32_16x16x32_bf16 v[44:47], v[128:131], v[116:119], v[44:47]
	ds_read_b64_tr_b16 v[128:129], v202 offset:9344
	ds_read_b64_tr_b16 v[130:131], v202 offset:13952
	s_waitcnt lgkmcnt(6)
	v_mfma_f32_16x16x32_bf16 v[72:75], v[132:135], v[100:103], v[72:75]
	v_mfma_f32_16x16x32_bf16 v[44:47], v[132:135], v[112:115], v[44:47]
	ds_read_b64_tr_b16 v[132:133], v202 offset:18560
	ds_read_b64_tr_b16 v[134:135], v202 offset:23168
	s_waitcnt lgkmcnt(6)
	v_mfma_f32_16x16x32_bf16 v[72:75], v[136:139], v[92:95], v[72:75]
	v_mfma_f32_16x16x32_bf16 v[44:47], v[136:139], v[84:87], v[44:47]
	ds_read_b64_tr_b16 v[136:137], v202 offset:27776
	ds_read_b64_tr_b16 v[138:139], v202 offset:32384
	s_waitcnt lgkmcnt(6)
	v_mfma_f32_16x16x32_bf16 v[76:79], v[124:127], v[108:111], v[76:79]
	v_mfma_f32_16x16x32_bf16 v[48:51], v[124:127], v[120:123], v[48:51]
	ds_read_b64_tr_b16 v[124:125], v202 offset:160
	ds_read_b64_tr_b16 v[126:127], v202 offset:4768
	s_waitcnt lgkmcnt(6)
	v_mfma_f32_16x16x32_bf16 v[76:79], v[128:131], v[104:107], v[76:79]
	v_mfma_f32_16x16x32_bf16 v[48:51], v[128:131], v[116:119], v[48:51]
	ds_read_b64_tr_b16 v[128:129], v202 offset:9376
	ds_read_b64_tr_b16 v[130:131], v202 offset:13984
	s_waitcnt lgkmcnt(6)
	v_mfma_f32_16x16x32_bf16 v[76:79], v[132:135], v[100:103], v[76:79]
	v_mfma_f32_16x16x32_bf16 v[48:51], v[132:135], v[112:115], v[48:51]
	ds_read_b64_tr_b16 v[132:133], v202 offset:18592
	ds_read_b64_tr_b16 v[134:135], v202 offset:23200
	s_waitcnt lgkmcnt(6)
	v_mfma_f32_16x16x32_bf16 v[76:79], v[136:139], v[92:95], v[76:79]
	v_mfma_f32_16x16x32_bf16 v[48:51], v[136:139], v[84:87], v[48:51]
	ds_read_b64_tr_b16 v[136:137], v202 offset:27808
	ds_read_b64_tr_b16 v[138:139], v202 offset:32416
	s_waitcnt lgkmcnt(6)
	v_mfma_f32_16x16x32_bf16 v[80:83], v[124:127], v[108:111], v[80:83]
	v_mfma_f32_16x16x32_bf16 v[52:55], v[124:127], v[120:123], v[52:55]
	ds_read_b64_tr_b16 v[124:125], v202 offset:192
	ds_read_b64_tr_b16 v[126:127], v202 offset:4800
	s_waitcnt lgkmcnt(6)
	v_mfma_f32_16x16x32_bf16 v[80:83], v[128:131], v[104:107], v[80:83]
	v_mfma_f32_16x16x32_bf16 v[52:55], v[128:131], v[116:119], v[52:55]
	ds_read_b64_tr_b16 v[128:129], v202 offset:9408
	ds_read_b64_tr_b16 v[130:131], v202 offset:14016
	s_waitcnt lgkmcnt(6)
	v_mfma_f32_16x16x32_bf16 v[80:83], v[132:135], v[100:103], v[80:83]
	v_mfma_f32_16x16x32_bf16 v[52:55], v[132:135], v[112:115], v[52:55]
	ds_read_b64_tr_b16 v[132:133], v202 offset:18624
	ds_read_b64_tr_b16 v[134:135], v202 offset:23232
	s_waitcnt lgkmcnt(6)
	v_mfma_f32_16x16x32_bf16 v[80:83], v[136:139], v[92:95], v[80:83]
	v_mfma_f32_16x16x32_bf16 v[52:55], v[136:139], v[84:87], v[52:55]
	ds_read_b64_tr_b16 v[136:137], v202 offset:27840
	ds_read_b64_tr_b16 v[138:139], v202 offset:32448
	s_waitcnt lgkmcnt(6)
	v_mfma_f32_16x16x32_bf16 v[88:91], v[124:127], v[108:111], v[88:91]
	v_mfma_f32_16x16x32_bf16 v[56:59], v[124:127], v[120:123], v[56:59]
	ds_read_b64_tr_b16 v[124:125], v202 offset:224
	ds_read_b64_tr_b16 v[126:127], v202 offset:4832
	s_waitcnt lgkmcnt(6)
	v_mfma_f32_16x16x32_bf16 v[88:91], v[128:131], v[104:107], v[88:91]
	v_mfma_f32_16x16x32_bf16 v[56:59], v[128:131], v[116:119], v[56:59]
	ds_read_b64_tr_b16 v[128:129], v202 offset:9440
	ds_read_b64_tr_b16 v[130:131], v202 offset:14048
	s_waitcnt lgkmcnt(6)
	v_mfma_f32_16x16x32_bf16 v[88:91], v[132:135], v[100:103], v[88:91]
	v_mfma_f32_16x16x32_bf16 v[56:59], v[132:135], v[112:115], v[56:59]
	ds_read_b64_tr_b16 v[132:133], v202 offset:18656
	ds_read_b64_tr_b16 v[134:135], v202 offset:23264
	s_waitcnt lgkmcnt(6)
	v_mfma_f32_16x16x32_bf16 v[88:91], v[136:139], v[92:95], v[88:91]
	v_mfma_f32_16x16x32_bf16 v[56:59], v[136:139], v[84:87], v[56:59]
	ds_read_b64_tr_b16 v[136:137], v202 offset:27872
	ds_read_b64_tr_b16 v[138:139], v202 offset:32480
	s_waitcnt lgkmcnt(6)
	v_mfma_f32_16x16x32_bf16 v[96:99], v[124:127], v[108:111], v[96:99]
	v_mfma_f32_16x16x32_bf16 v[108:111], v[124:127], v[120:123], v[144:147]
	s_waitcnt lgkmcnt(4)
	v_mfma_f32_16x16x32_bf16 v[96:99], v[128:131], v[104:107], v[96:99]
	v_mfma_f32_16x16x32_bf16 v[104:107], v[128:131], v[116:119], v[108:111]
	s_waitcnt lgkmcnt(2)
	v_mfma_f32_16x16x32_bf16 v[96:99], v[132:135], v[100:103], v[96:99]
	v_mfma_f32_16x16x32_bf16 v[100:103], v[132:135], v[112:115], v[104:107]
	s_waitcnt lgkmcnt(0)
	v_mfma_f32_16x16x32_bf16 v[96:99], v[136:139], v[92:95], v[96:99]
	v_mfma_f32_16x16x32_bf16 v[84:87], v[136:139], v[84:87], v[100:103]
	s_cbranch_vccnz .LBB0_614
	v_mov_b32_e32 v209, v207
	v_mov_b32_e32 v208, v148
	s_cmp_eq_u32 s51, 0
	s_cbranch_scc0 .LBB0_605
	s_branch .LBB0_606
